# retention chunk gate-multiply store pass: eight row-chunk loads in flight instead of serialised load-wait-store
# speedup vs baseline: 1.0421x; 1.0055x over previous
.LBB0_964:
	s_or_b64 exec, exec, s[82:83]
	v_or_b32_e32 v128, 0x24000, v205
	s_waitcnt lgkmcnt(0)
	s_barrier
	ds_read_b64 v[128:129], v128
	s_mov_b32 s82, 0
	s_waitcnt lgkmcnt(0)
	v_pk_add_f32 v[112:113], v[112:113], v[128:129] op_sel_hi:[1,0] neg_lo:[0,1] neg_hi:[0,1]
	v_pk_add_f32 v[114:115], v[114:115], v[128:129] op_sel_hi:[1,0] neg_lo:[0,1] neg_hi:[0,1]
	v_pk_mul_f32 v[112:113], v[128:129], v[112:113] op_sel:[1,0]
	v_pk_mul_f32 v[114:115], v[128:129], v[114:115] op_sel:[1,0]
	v_cvt_pk_bf16_f32 v112, v112, v113
	v_cvt_pk_bf16_f32 v113, v114, v115
	v_pk_add_f32 v[114:115], v[116:117], v[128:129] op_sel_hi:[1,0] neg_lo:[0,1] neg_hi:[0,1]
	v_pk_add_f32 v[116:117], v[118:119], v[128:129] op_sel_hi:[1,0] neg_lo:[0,1] neg_hi:[0,1]
	v_pk_mul_f32 v[114:115], v[128:129], v[114:115] op_sel:[1,0]
	v_pk_mul_f32 v[116:117], v[128:129], v[116:117] op_sel:[1,0]
	v_cvt_pk_bf16_f32 v114, v114, v115
	v_cvt_pk_bf16_f32 v115, v116, v117
	ds_write2_b64 v245, v[112:113], v[114:115] offset1:2
	v_pk_add_f32 v[112:113], v[120:121], v[128:129] op_sel_hi:[1,0] neg_lo:[0,1] neg_hi:[0,1]
	v_pk_add_f32 v[114:115], v[122:123], v[128:129] op_sel_hi:[1,0] neg_lo:[0,1] neg_hi:[0,1]
	v_pk_mul_f32 v[112:113], v[128:129], v[112:113] op_sel:[1,0]
	v_pk_mul_f32 v[114:115], v[128:129], v[114:115] op_sel:[1,0]
	v_cvt_pk_bf16_f32 v112, v112, v113
	v_cvt_pk_bf16_f32 v113, v114, v115
	v_pk_add_f32 v[114:115], v[124:125], v[128:129] op_sel_hi:[1,0] neg_lo:[0,1] neg_hi:[0,1]
	v_pk_add_f32 v[116:117], v[126:127], v[128:129] op_sel_hi:[1,0] neg_lo:[0,1] neg_hi:[0,1]
	v_pk_mul_f32 v[114:115], v[128:129], v[114:115] op_sel:[1,0]
	v_pk_mul_f32 v[116:117], v[128:129], v[116:117] op_sel:[1,0]
	v_cvt_pk_bf16_f32 v114, v114, v115
	v_cvt_pk_bf16_f32 v115, v116, v117
	ds_write2_b64 v245, v[112:113], v[114:115] offset0:4 offset1:6
	ds_read_b64 v[112:113], v246
	s_waitcnt lgkmcnt(0)
	v_pk_add_f32 v[96:97], v[96:97], v[112:113] op_sel_hi:[1,0] neg_lo:[0,1] neg_hi:[0,1]
	v_pk_add_f32 v[98:99], v[98:99], v[112:113] op_sel_hi:[1,0] neg_lo:[0,1] neg_hi:[0,1]
	v_pk_mul_f32 v[96:97], v[112:113], v[96:97] op_sel:[1,0]
	v_pk_mul_f32 v[98:99], v[112:113], v[98:99] op_sel:[1,0]
	v_cvt_pk_bf16_f32 v96, v96, v97
	v_cvt_pk_bf16_f32 v97, v98, v99
	v_pk_add_f32 v[98:99], v[100:101], v[112:113] op_sel_hi:[1,0] neg_lo:[0,1] neg_hi:[0,1]
	v_pk_add_f32 v[100:101], v[102:103], v[112:113] op_sel_hi:[1,0] neg_lo:[0,1] neg_hi:[0,1]
	v_pk_mul_f32 v[98:99], v[112:113], v[98:99] op_sel:[1,0]
	v_pk_mul_f32 v[100:101], v[112:113], v[100:101] op_sel:[1,0]
	v_cvt_pk_bf16_f32 v98, v98, v99
	v_cvt_pk_bf16_f32 v99, v100, v101
	v_add_u32_e32 v102, 0x4000, v245
	ds_write2_b64 v102, v[96:97], v[98:99] offset0:64 offset1:66
	v_pk_add_f32 v[96:97], v[104:105], v[112:113] op_sel_hi:[1,0] neg_lo:[0,1] neg_hi:[0,1]
	v_pk_add_f32 v[98:99], v[106:107], v[112:113] op_sel_hi:[1,0] neg_lo:[0,1] neg_hi:[0,1]
	v_pk_mul_f32 v[96:97], v[112:113], v[96:97] op_sel:[1,0]
	v_pk_mul_f32 v[98:99], v[112:113], v[98:99] op_sel:[1,0]
	v_cvt_pk_bf16_f32 v96, v96, v97
	v_cvt_pk_bf16_f32 v97, v98, v99
	v_pk_add_f32 v[98:99], v[108:109], v[112:113] op_sel_hi:[1,0] neg_lo:[0,1] neg_hi:[0,1]
	v_pk_add_f32 v[100:101], v[110:111], v[112:113] op_sel_hi:[1,0] neg_lo:[0,1] neg_hi:[0,1]
	v_pk_mul_f32 v[98:99], v[112:113], v[98:99] op_sel:[1,0]
	v_pk_mul_f32 v[100:101], v[112:113], v[100:101] op_sel:[1,0]
	v_cvt_pk_bf16_f32 v98, v98, v99
	v_cvt_pk_bf16_f32 v99, v100, v101
	ds_write2_b64 v102, v[96:97], v[98:99] offset0:68 offset1:70
	ds_read_b64 v[96:97], v247
	s_waitcnt lgkmcnt(0)
	v_pk_add_f32 v[80:81], v[80:81], v[96:97] op_sel_hi:[1,0] neg_lo:[0,1] neg_hi:[0,1]
	v_pk_add_f32 v[82:83], v[82:83], v[96:97] op_sel_hi:[1,0] neg_lo:[0,1] neg_hi:[0,1]
	v_pk_mul_f32 v[80:81], v[96:97], v[80:81] op_sel:[1,0]
	v_pk_mul_f32 v[82:83], v[96:97], v[82:83] op_sel:[1,0]
	v_cvt_pk_bf16_f32 v80, v80, v81
	v_cvt_pk_bf16_f32 v81, v82, v83
	v_pk_add_f32 v[82:83], v[84:85], v[96:97] op_sel_hi:[1,0] neg_lo:[0,1] neg_hi:[0,1]
	v_pk_add_f32 v[84:85], v[86:87], v[96:97] op_sel_hi:[1,0] neg_lo:[0,1] neg_hi:[0,1]
	v_pk_mul_f32 v[82:83], v[96:97], v[82:83] op_sel:[1,0]
	v_pk_mul_f32 v[84:85], v[96:97], v[84:85] op_sel:[1,0]
	v_cvt_pk_bf16_f32 v82, v82, v83
	v_cvt_pk_bf16_f32 v83, v84, v85
	v_add_u32_e32 v86, 0x8000, v245
	ds_write2_b64 v86, v[80:81], v[82:83] offset0:128 offset1:130
	v_pk_add_f32 v[80:81], v[88:89], v[96:97] op_sel_hi:[1,0] neg_lo:[0,1] neg_hi:[0,1]
	v_pk_add_f32 v[82:83], v[90:91], v[96:97] op_sel_hi:[1,0] neg_lo:[0,1] neg_hi:[0,1]
	v_pk_mul_f32 v[80:81], v[96:97], v[80:81] op_sel:[1,0]
	v_pk_mul_f32 v[82:83], v[96:97], v[82:83] op_sel:[1,0]
	v_cvt_pk_bf16_f32 v80, v80, v81
	v_cvt_pk_bf16_f32 v81, v82, v83
	v_pk_add_f32 v[82:83], v[92:93], v[96:97] op_sel_hi:[1,0] neg_lo:[0,1] neg_hi:[0,1]
	v_pk_add_f32 v[84:85], v[94:95], v[96:97] op_sel_hi:[1,0] neg_lo:[0,1] neg_hi:[0,1]
	v_pk_mul_f32 v[82:83], v[96:97], v[82:83] op_sel:[1,0]
	v_pk_mul_f32 v[84:85], v[96:97], v[84:85] op_sel:[1,0]
	v_cvt_pk_bf16_f32 v82, v82, v83
	v_cvt_pk_bf16_f32 v83, v84, v85
	ds_write2_b64 v86, v[80:81], v[82:83] offset0:132 offset1:134
	ds_read_b64 v[80:81], v248
	s_waitcnt lgkmcnt(0)
	v_pk_add_f32 v[64:65], v[64:65], v[80:81] op_sel_hi:[1,0] neg_lo:[0,1] neg_hi:[0,1]
	v_pk_add_f32 v[66:67], v[66:67], v[80:81] op_sel_hi:[1,0] neg_lo:[0,1] neg_hi:[0,1]
	v_pk_mul_f32 v[64:65], v[80:81], v[64:65] op_sel:[1,0]
	v_pk_mul_f32 v[66:67], v[80:81], v[66:67] op_sel:[1,0]
	v_cvt_pk_bf16_f32 v64, v64, v65
	v_cvt_pk_bf16_f32 v65, v66, v67
	v_pk_add_f32 v[66:67], v[68:69], v[80:81] op_sel_hi:[1,0] neg_lo:[0,1] neg_hi:[0,1]
	v_pk_add_f32 v[68:69], v[70:71], v[80:81] op_sel_hi:[1,0] neg_lo:[0,1] neg_hi:[0,1]
	v_pk_mul_f32 v[66:67], v[80:81], v[66:67] op_sel:[1,0]
	v_pk_mul_f32 v[68:69], v[80:81], v[68:69] op_sel:[1,0]
	v_cvt_pk_bf16_f32 v66, v66, v67
	v_cvt_pk_bf16_f32 v67, v68, v69
	v_add_u32_e32 v70, 0xc000, v245
	ds_write2_b64 v70, v[64:65], v[66:67] offset0:192 offset1:194
	v_pk_add_f32 v[64:65], v[72:73], v[80:81] op_sel_hi:[1,0] neg_lo:[0,1] neg_hi:[0,1]
	v_pk_add_f32 v[66:67], v[74:75], v[80:81] op_sel_hi:[1,0] neg_lo:[0,1] neg_hi:[0,1]
	v_pk_mul_f32 v[64:65], v[80:81], v[64:65] op_sel:[1,0]
	v_pk_mul_f32 v[66:67], v[80:81], v[66:67] op_sel:[1,0]
	v_cvt_pk_bf16_f32 v64, v64, v65
	v_cvt_pk_bf16_f32 v65, v66, v67
	v_pk_add_f32 v[66:67], v[76:77], v[80:81] op_sel_hi:[1,0] neg_lo:[0,1] neg_hi:[0,1]
	v_pk_add_f32 v[68:69], v[78:79], v[80:81] op_sel_hi:[1,0] neg_lo:[0,1] neg_hi:[0,1]
	v_pk_mul_f32 v[66:67], v[80:81], v[66:67] op_sel:[1,0]
	v_pk_mul_f32 v[68:69], v[80:81], v[68:69] op_sel:[1,0]
	v_cvt_pk_bf16_f32 v66, v66, v67
	v_cvt_pk_bf16_f32 v67, v68, v69
	ds_write2_b64 v70, v[64:65], v[66:67] offset0:196 offset1:198
	s_waitcnt lgkmcnt(0)
	s_barrier
	s_mov_b32 s98, 0xffff0000
	v_ashrrev_i32_e32 v120, 5, v191
	v_add_u32_e32 v121, s3, v120
	v_lshlrev_b32_e32 v121, 11, v121
	v_subrev_u32_e32 v122, s96, v150
	v_add_u32_e32 v122, v122, v121
	v_mad_u32_u24 v123, v120, s1, v148
	v_add_u32_e32 v124, 0x0, v122
	global_load_dwordx4 v[64:67], v124, s[96:97]
	ds_read_b128 v[96:99], v123
	v_add_u32_e32 v124, 0x8000, v122
	global_load_dwordx4 v[68:71], v124, s[96:97]
	ds_read_b128 v[100:103], v123 offset:8448
	v_add_u32_e32 v124, 0x10000, v122
	global_load_dwordx4 v[72:75], v124, s[96:97]
	ds_read_b128 v[104:107], v123 offset:16896
	v_add_u32_e32 v124, 0x18000, v122
	global_load_dwordx4 v[76:79], v124, s[96:97]
	ds_read_b128 v[108:111], v123 offset:25344
	v_add_u32_e32 v124, 0x20000, v122
	global_load_dwordx4 v[80:83], v124, s[96:97]
	v_add_u32_e32 v124, 0x28000, v122
	global_load_dwordx4 v[84:87], v124, s[96:97]
	v_add_u32_e32 v124, 0x30000, v122
	global_load_dwordx4 v[88:91], v124, s[96:97]
	v_add_u32_e32 v124, 0x38000, v122
	global_load_dwordx4 v[92:95], v124, s[96:97]
	s_waitcnt vmcnt(7) lgkmcnt(3)
	v_lshlrev_b32_e32 v112, 16, v96
	v_and_b32_e32 v113, s98, v96
	v_lshlrev_b32_e32 v114, 16, v64
	v_and_b32_e32 v115, s98, v64
	v_lshlrev_b32_e32 v116, 16, v97
	v_and_b32_e32 v117, s98, v97
	v_lshlrev_b32_e32 v118, 16, v65
	v_and_b32_e32 v119, s98, v65
	v_pk_mul_f32 v[112:113], v[112:113], v[114:115]
	v_pk_mul_f32 v[116:117], v[116:117], v[118:119]
	v_cvt_pk_bf16_f32 v64, v112, v113
	v_cvt_pk_bf16_f32 v65, v116, v117
	v_lshlrev_b32_e32 v112, 16, v98
	v_and_b32_e32 v113, s98, v98
	v_lshlrev_b32_e32 v114, 16, v66
	v_and_b32_e32 v115, s98, v66
	v_lshlrev_b32_e32 v116, 16, v99
	v_and_b32_e32 v117, s98, v99
	v_lshlrev_b32_e32 v118, 16, v67
	v_and_b32_e32 v119, s98, v67
	v_pk_mul_f32 v[112:113], v[112:113], v[114:115]
	v_pk_mul_f32 v[116:117], v[116:117], v[118:119]
	v_cvt_pk_bf16_f32 v66, v112, v113
	v_cvt_pk_bf16_f32 v67, v116, v117
	ds_read_b128 v[96:99], v123 offset:33792
	v_add_u32_e32 v125, 0x0, v122
	global_store_dwordx4 v125, v[64:67], s[96:97]
	s_waitcnt vmcnt(7) lgkmcnt(3)
	v_lshlrev_b32_e32 v112, 16, v100
	v_and_b32_e32 v113, s98, v100
	v_lshlrev_b32_e32 v114, 16, v68
	v_and_b32_e32 v115, s98, v68
	v_lshlrev_b32_e32 v116, 16, v101
	v_and_b32_e32 v117, s98, v101
	v_lshlrev_b32_e32 v118, 16, v69
	v_and_b32_e32 v119, s98, v69
	v_pk_mul_f32 v[112:113], v[112:113], v[114:115]
	v_pk_mul_f32 v[116:117], v[116:117], v[118:119]
	v_cvt_pk_bf16_f32 v68, v112, v113
	v_cvt_pk_bf16_f32 v69, v116, v117
	v_lshlrev_b32_e32 v112, 16, v102
	v_and_b32_e32 v113, s98, v102
	v_lshlrev_b32_e32 v114, 16, v70
	v_and_b32_e32 v115, s98, v70
	v_lshlrev_b32_e32 v116, 16, v103
	v_and_b32_e32 v117, s98, v103
	v_lshlrev_b32_e32 v118, 16, v71
	v_and_b32_e32 v119, s98, v71
	v_pk_mul_f32 v[112:113], v[112:113], v[114:115]
	v_pk_mul_f32 v[116:117], v[116:117], v[118:119]
	v_cvt_pk_bf16_f32 v70, v112, v113
	v_cvt_pk_bf16_f32 v71, v116, v117
	ds_read_b128 v[100:103], v123 offset:42240
	v_add_u32_e32 v125, 0x8000, v122
	global_store_dwordx4 v125, v[68:71], s[96:97]
	s_waitcnt vmcnt(7) lgkmcnt(3)
	v_lshlrev_b32_e32 v112, 16, v104
	v_and_b32_e32 v113, s98, v104
	v_lshlrev_b32_e32 v114, 16, v72
	v_and_b32_e32 v115, s98, v72
	v_lshlrev_b32_e32 v116, 16, v105
	v_and_b32_e32 v117, s98, v105
	v_lshlrev_b32_e32 v118, 16, v73
	v_and_b32_e32 v119, s98, v73
	v_pk_mul_f32 v[112:113], v[112:113], v[114:115]
	v_pk_mul_f32 v[116:117], v[116:117], v[118:119]
	v_cvt_pk_bf16_f32 v72, v112, v113
	v_cvt_pk_bf16_f32 v73, v116, v117
	v_lshlrev_b32_e32 v112, 16, v106
	v_and_b32_e32 v113, s98, v106
	v_lshlrev_b32_e32 v114, 16, v74
	v_and_b32_e32 v115, s98, v74
	v_lshlrev_b32_e32 v116, 16, v107
	v_and_b32_e32 v117, s98, v107
	v_lshlrev_b32_e32 v118, 16, v75
	v_and_b32_e32 v119, s98, v75
	v_pk_mul_f32 v[112:113], v[112:113], v[114:115]
	v_pk_mul_f32 v[116:117], v[116:117], v[118:119]
	v_cvt_pk_bf16_f32 v74, v112, v113
	v_cvt_pk_bf16_f32 v75, v116, v117
	ds_read_b128 v[104:107], v123 offset:50688
	v_add_u32_e32 v125, 0x10000, v122
	global_store_dwordx4 v125, v[72:75], s[96:97]
	s_waitcnt vmcnt(7) lgkmcnt(3)
	v_lshlrev_b32_e32 v112, 16, v108
	v_and_b32_e32 v113, s98, v108
	v_lshlrev_b32_e32 v114, 16, v76
	v_and_b32_e32 v115, s98, v76
	v_lshlrev_b32_e32 v116, 16, v109
	v_and_b32_e32 v117, s98, v109
	v_lshlrev_b32_e32 v118, 16, v77
	v_and_b32_e32 v119, s98, v77
	v_pk_mul_f32 v[112:113], v[112:113], v[114:115]
	v_pk_mul_f32 v[116:117], v[116:117], v[118:119]
	v_cvt_pk_bf16_f32 v76, v112, v113
	v_cvt_pk_bf16_f32 v77, v116, v117
	v_lshlrev_b32_e32 v112, 16, v110
	v_and_b32_e32 v113, s98, v110
	v_lshlrev_b32_e32 v114, 16, v78
	v_and_b32_e32 v115, s98, v78
	v_lshlrev_b32_e32 v116, 16, v111
	v_and_b32_e32 v117, s98, v111
	v_lshlrev_b32_e32 v118, 16, v79
	v_and_b32_e32 v119, s98, v79
	v_pk_mul_f32 v[112:113], v[112:113], v[114:115]
	v_pk_mul_f32 v[116:117], v[116:117], v[118:119]
	v_cvt_pk_bf16_f32 v78, v112, v113
	v_cvt_pk_bf16_f32 v79, v116, v117
	ds_read_b128 v[108:111], v123 offset:59136
	v_add_u32_e32 v125, 0x18000, v122
	global_store_dwordx4 v125, v[76:79], s[96:97]
	s_waitcnt vmcnt(7) lgkmcnt(3)
	v_lshlrev_b32_e32 v112, 16, v96
	v_and_b32_e32 v113, s98, v96
	v_lshlrev_b32_e32 v114, 16, v80
	v_and_b32_e32 v115, s98, v80
	v_lshlrev_b32_e32 v116, 16, v97
	v_and_b32_e32 v117, s98, v97
	v_lshlrev_b32_e32 v118, 16, v81
	v_and_b32_e32 v119, s98, v81
	v_pk_mul_f32 v[112:113], v[112:113], v[114:115]
	v_pk_mul_f32 v[116:117], v[116:117], v[118:119]
	v_cvt_pk_bf16_f32 v80, v112, v113
	v_cvt_pk_bf16_f32 v81, v116, v117
	v_lshlrev_b32_e32 v112, 16, v98
	v_and_b32_e32 v113, s98, v98
	v_lshlrev_b32_e32 v114, 16, v82
	v_and_b32_e32 v115, s98, v82
	v_lshlrev_b32_e32 v116, 16, v99
	v_and_b32_e32 v117, s98, v99
	v_lshlrev_b32_e32 v118, 16, v83
	v_and_b32_e32 v119, s98, v83
	v_pk_mul_f32 v[112:113], v[112:113], v[114:115]
	v_pk_mul_f32 v[116:117], v[116:117], v[118:119]
	v_cvt_pk_bf16_f32 v82, v112, v113
	v_cvt_pk_bf16_f32 v83, v116, v117
	v_add_u32_e32 v125, 0x20000, v122
	global_store_dwordx4 v125, v[80:83], s[96:97]
	s_waitcnt vmcnt(7) lgkmcnt(2)
	v_lshlrev_b32_e32 v112, 16, v100
	v_and_b32_e32 v113, s98, v100
	v_lshlrev_b32_e32 v114, 16, v84
	v_and_b32_e32 v115, s98, v84
	v_lshlrev_b32_e32 v116, 16, v101
	v_and_b32_e32 v117, s98, v101
	v_lshlrev_b32_e32 v118, 16, v85
	v_and_b32_e32 v119, s98, v85
	v_pk_mul_f32 v[112:113], v[112:113], v[114:115]
	v_pk_mul_f32 v[116:117], v[116:117], v[118:119]
	v_cvt_pk_bf16_f32 v84, v112, v113
	v_cvt_pk_bf16_f32 v85, v116, v117
	v_lshlrev_b32_e32 v112, 16, v102
	v_and_b32_e32 v113, s98, v102
	v_lshlrev_b32_e32 v114, 16, v86
	v_and_b32_e32 v115, s98, v86
	v_lshlrev_b32_e32 v116, 16, v103
	v_and_b32_e32 v117, s98, v103
	v_lshlrev_b32_e32 v118, 16, v87
	v_and_b32_e32 v119, s98, v87
	v_pk_mul_f32 v[112:113], v[112:113], v[114:115]
	v_pk_mul_f32 v[116:117], v[116:117], v[118:119]
	v_cvt_pk_bf16_f32 v86, v112, v113
	v_cvt_pk_bf16_f32 v87, v116, v117
	v_add_u32_e32 v125, 0x28000, v122
	global_store_dwordx4 v125, v[84:87], s[96:97]
	s_waitcnt vmcnt(7) lgkmcnt(1)
	v_lshlrev_b32_e32 v112, 16, v104
	v_and_b32_e32 v113, s98, v104
	v_lshlrev_b32_e32 v114, 16, v88
	v_and_b32_e32 v115, s98, v88
	v_lshlrev_b32_e32 v116, 16, v105
	v_and_b32_e32 v117, s98, v105
	v_lshlrev_b32_e32 v118, 16, v89
	v_and_b32_e32 v119, s98, v89
	v_pk_mul_f32 v[112:113], v[112:113], v[114:115]
	v_pk_mul_f32 v[116:117], v[116:117], v[118:119]
	v_cvt_pk_bf16_f32 v88, v112, v113
	v_cvt_pk_bf16_f32 v89, v116, v117
	v_lshlrev_b32_e32 v112, 16, v106
	v_and_b32_e32 v113, s98, v106
	v_lshlrev_b32_e32 v114, 16, v90
	v_and_b32_e32 v115, s98, v90
	v_lshlrev_b32_e32 v116, 16, v107
	v_and_b32_e32 v117, s98, v107
	v_lshlrev_b32_e32 v118, 16, v91
	v_and_b32_e32 v119, s98, v91
	v_pk_mul_f32 v[112:113], v[112:113], v[114:115]
	v_pk_mul_f32 v[116:117], v[116:117], v[118:119]
	v_cvt_pk_bf16_f32 v90, v112, v113
	v_cvt_pk_bf16_f32 v91, v116, v117
	v_add_u32_e32 v125, 0x30000, v122
	global_store_dwordx4 v125, v[88:91], s[96:97]
	s_waitcnt vmcnt(7) lgkmcnt(0)
	v_lshlrev_b32_e32 v112, 16, v108
	v_and_b32_e32 v113, s98, v108
	v_lshlrev_b32_e32 v114, 16, v92
	v_and_b32_e32 v115, s98, v92
	v_lshlrev_b32_e32 v116, 16, v109
	v_and_b32_e32 v117, s98, v109
	v_lshlrev_b32_e32 v118, 16, v93
	v_and_b32_e32 v119, s98, v93
	v_pk_mul_f32 v[112:113], v[112:113], v[114:115]
	v_pk_mul_f32 v[116:117], v[116:117], v[118:119]
	v_cvt_pk_bf16_f32 v92, v112, v113
	v_cvt_pk_bf16_f32 v93, v116, v117
	v_lshlrev_b32_e32 v112, 16, v110
	v_and_b32_e32 v113, s98, v110
	v_lshlrev_b32_e32 v114, 16, v94
	v_and_b32_e32 v115, s98, v94
	v_lshlrev_b32_e32 v116, 16, v111
	v_and_b32_e32 v117, s98, v111
	v_lshlrev_b32_e32 v118, 16, v95
	v_and_b32_e32 v119, s98, v95
	v_pk_mul_f32 v[112:113], v[112:113], v[114:115]
	v_pk_mul_f32 v[116:117], v[116:117], v[118:119]
	v_cvt_pk_bf16_f32 v94, v112, v113
	v_cvt_pk_bf16_f32 v95, v116, v117
	v_add_u32_e32 v125, 0x38000, v122
	global_store_dwordx4 v125, v[92:95], s[96:97]
	s_movk_i32 s82, 0x1000
	s_add_i32 s94, s94, 1
	s_cmp_eq_u32 s94, 16
	s_cbranch_scc0 .LBB0_939
